# conv stage of P3/P5 items: second round's 12 token rows prefetched into a stash register set right after the first round's rows arrive (clamped row index), nop pads keep the GEMM loop heads at the pre
# baseline (speedup 1.0000x reference)
.LBB0_652:
	s_or_b64 exec, exec, s[0:1]
	s_waitcnt vmcnt(0)
	v_add_u32_e32 v252, s46, v166
	v_add_u32_e32 v250, 8, v252
	v_min_i32_e32 v250, 0x4fff, v250
	v_mov_b32_e32 v251, 0
	v_lshlrev_b64 v[250:251], 12, v[250:251]
	v_lshl_add_u64 v[250:251], v[100:101], 0, v[250:251]
	global_load_dwordx4 v[200:203], v[250:251], off
	v_add_u32_e32 v250, 9, v252
	v_min_i32_e32 v250, 0x4fff, v250
	v_mov_b32_e32 v251, 0
	v_lshlrev_b64 v[250:251], 12, v[250:251]
	v_lshl_add_u64 v[250:251], v[100:101], 0, v[250:251]
	global_load_dwordx4 v[204:207], v[250:251], off
	v_add_u32_e32 v250, 10, v252
	v_min_i32_e32 v250, 0x4fff, v250
	v_mov_b32_e32 v251, 0
	v_lshlrev_b64 v[250:251], 12, v[250:251]
	v_lshl_add_u64 v[250:251], v[100:101], 0, v[250:251]
	global_load_dwordx4 v[208:211], v[250:251], off
	v_add_u32_e32 v250, 11, v252
	v_min_i32_e32 v250, 0x4fff, v250
	v_mov_b32_e32 v251, 0
	v_lshlrev_b64 v[250:251], 12, v[250:251]
	v_lshl_add_u64 v[250:251], v[100:101], 0, v[250:251]
	global_load_dwordx4 v[212:215], v[250:251], off
	v_add_u32_e32 v250, 12, v252
	v_min_i32_e32 v250, 0x4fff, v250
	v_mov_b32_e32 v251, 0
	v_lshlrev_b64 v[250:251], 12, v[250:251]
	v_lshl_add_u64 v[250:251], v[100:101], 0, v[250:251]
	global_load_dwordx4 v[216:219], v[250:251], off
	v_add_u32_e32 v250, 13, v252
	v_min_i32_e32 v250, 0x4fff, v250
	v_mov_b32_e32 v251, 0
	v_lshlrev_b64 v[250:251], 12, v[250:251]
	v_lshl_add_u64 v[250:251], v[100:101], 0, v[250:251]
	global_load_dwordx4 v[220:223], v[250:251], off
	v_add_u32_e32 v250, 14, v252
	v_min_i32_e32 v250, 0x4fff, v250
	v_mov_b32_e32 v251, 0
	v_lshlrev_b64 v[250:251], 12, v[250:251]
	v_lshl_add_u64 v[250:251], v[100:101], 0, v[250:251]
	global_load_dwordx4 v[224:227], v[250:251], off
	v_add_u32_e32 v250, 15, v252
	v_min_i32_e32 v250, 0x4fff, v250
	v_mov_b32_e32 v251, 0
	v_lshlrev_b64 v[250:251], 12, v[250:251]
	v_lshl_add_u64 v[250:251], v[100:101], 0, v[250:251]
	global_load_dwordx4 v[228:231], v[250:251], off
	v_add_u32_e32 v250, 16, v252
	v_min_i32_e32 v250, 0x4fff, v250
	v_mov_b32_e32 v251, 0
	v_lshlrev_b64 v[250:251], 12, v[250:251]
	v_lshl_add_u64 v[250:251], v[100:101], 0, v[250:251]
	global_load_dwordx4 v[232:235], v[250:251], off
	v_add_u32_e32 v250, 17, v252
	v_min_i32_e32 v250, 0x4fff, v250
	v_mov_b32_e32 v251, 0
	v_lshlrev_b64 v[250:251], 12, v[250:251]
	v_lshl_add_u64 v[250:251], v[100:101], 0, v[250:251]
	global_load_dwordx4 v[236:239], v[250:251], off
	v_add_u32_e32 v250, 18, v252
	v_min_i32_e32 v250, 0x4fff, v250
	v_mov_b32_e32 v251, 0
	v_lshlrev_b64 v[250:251], 12, v[250:251]
	v_lshl_add_u64 v[250:251], v[100:101], 0, v[250:251]
	global_load_dwordx4 v[240:243], v[250:251], off
	v_add_u32_e32 v250, 19, v252
	v_min_i32_e32 v250, 0x4fff, v250
	v_mov_b32_e32 v251, 0
	v_lshlrev_b64 v[250:251], 12, v[250:251]
	v_lshl_add_u64 v[250:251], v[100:101], 0, v[250:251]
	global_load_dwordx4 v[244:247], v[250:251], off
.Lcv3_go:
	v_lshlrev_b32_e32 v168, 16, v52
	v_and_b32_e32 v169, 0xffff0000, v52
	v_lshlrev_b32_e32 v170, 16, v53
	v_and_b32_e32 v171, 0xffff0000, v53
	v_lshlrev_b32_e32 v172, 16, v54
	v_and_b32_e32 v173, 0xffff0000, v54
	v_lshlrev_b32_e32 v174, 16, v55
	v_and_b32_e32 v175, 0xffff0000, v55
	v_lshlrev_b32_e32 v176, 16, v48
	v_and_b32_e32 v177, 0xffff0000, v48
	v_lshlrev_b32_e32 v148, 16, v49
	v_and_b32_e32 v149, 0xffff0000, v49
	v_lshlrev_b32_e32 v146, 16, v50
	v_and_b32_e32 v147, 0xffff0000, v50
	v_lshlrev_b32_e32 v144, 16, v51
	v_and_b32_e32 v145, 0xffff0000, v51
	v_lshlrev_b32_e32 v142, 16, v60
	v_and_b32_e32 v143, 0xffff0000, v60
	v_lshlrev_b32_e32 v140, 16, v61
	v_and_b32_e32 v141, 0xffff0000, v61
	v_lshlrev_b32_e32 v130, 16, v58
	v_and_b32_e32 v131, 0xffff0000, v58
	v_lshlrev_b32_e32 v128, 16, v59
	v_and_b32_e32 v129, 0xffff0000, v59
	v_lshlrev_b32_e32 v126, 16, v68
	v_and_b32_e32 v127, 0xffff0000, v68
	v_lshlrev_b32_e32 v124, 16, v69
	v_and_b32_e32 v125, 0xffff0000, v69
	v_lshlrev_b32_e32 v118, 16, v64
	v_and_b32_e32 v119, 0xffff0000, v64
	v_lshlrev_b32_e32 v116, 16, v65
	v_and_b32_e32 v117, 0xffff0000, v65
	v_lshlrev_b32_e32 v60, 16, v86
	v_and_b32_e32 v61, 0xffff0000, v86
	v_lshlrev_b32_e32 v50, 16, v87
	v_and_b32_e32 v51, 0xffff0000, v87
	v_lshlrev_b32_e32 v64, 16, v94
	v_and_b32_e32 v65, 0xffff0000, v94
	v_lshlrev_b32_e32 v54, 16, v95
	v_and_b32_e32 v55, 0xffff0000, v95
	v_lshlrev_b32_e32 v68, 16, v90
	v_and_b32_e32 v69, 0xffff0000, v90
	v_lshlrev_b32_e32 v58, 16, v91
	v_and_b32_e32 v59, 0xffff0000, v91
	v_pk_fma_f32 v[86:87], v[40:41], v[168:169], v[44:45]
	v_pk_fma_f32 v[90:91], v[42:43], v[170:171], v[46:47]
	v_pk_fma_f32 v[94:95], v[32:33], v[172:173], v[36:37]
	v_lshlrev_b32_e32 v138, 16, v62
	v_and_b32_e32 v139, 0xffff0000, v62
	v_pk_fma_f32 v[86:87], v[0:1], v[176:177], v[86:87]
	v_pk_fma_f32 v[90:91], v[2:3], v[148:149], v[90:91]
	v_pk_fma_f32 v[94:95], v[4:5], v[146:147], v[94:95]
	v_lshlrev_b32_e32 v134, 16, v56
	v_and_b32_e32 v135, 0xffff0000, v56
	v_lshlrev_b32_e32 v132, 16, v57
	v_and_b32_e32 v133, 0xffff0000, v57
	v_pk_fma_f32 v[86:87], v[8:9], v[142:143], v[86:87]
	v_pk_fma_f32 v[90:91], v[10:11], v[140:141], v[90:91]
	v_pk_fma_f32 v[94:95], v[12:13], v[138:139], v[94:95]
	v_pk_fma_f32 v[170:171], v[34:35], v[174:175], v[38:39]
	v_lshlrev_b32_e32 v136, 16, v63
	v_and_b32_e32 v137, 0xffff0000, v63
	v_lshlrev_b32_e32 v122, 16, v70
	v_and_b32_e32 v123, 0xffff0000, v70
	v_pk_fma_f32 v[86:87], v[16:17], v[134:135], v[86:87]
	v_pk_fma_f32 v[90:91], v[18:19], v[132:133], v[90:91]
	v_pk_fma_f32 v[94:95], v[20:21], v[130:131], v[94:95]
	v_pk_fma_f32 v[170:171], v[6:7], v[144:145], v[170:171]
	v_pk_fma_f32 v[86:87], v[24:25], v[126:127], v[86:87]
	v_pk_fma_f32 v[90:91], v[26:27], v[124:125], v[90:91]
	v_pk_fma_f32 v[94:95], v[28:29], v[122:123], v[94:95]
	v_pk_fma_f32 v[170:171], v[14:15], v[136:137], v[170:171]
	v_lshlrev_b32_e32 v120, 16, v71
	v_and_b32_e32 v121, 0xffff0000, v71
	v_lshlrev_b32_e32 v114, 16, v66
	v_and_b32_e32 v115, 0xffff0000, v66
	v_lshlrev_b32_e32 v112, 16, v67
	v_and_b32_e32 v113, 0xffff0000, v67
	v_lshlrev_b32_e32 v110, 16, v76
	v_and_b32_e32 v111, 0xffff0000, v76
	v_lshlrev_b32_e32 v108, 16, v77
	v_and_b32_e32 v109, 0xffff0000, v77
	v_lshlrev_b32_e32 v106, 16, v78
	v_and_b32_e32 v107, 0xffff0000, v78
	v_lshlrev_b32_e32 v104, 16, v79
	v_and_b32_e32 v105, 0xffff0000, v79
	v_lshlrev_b32_e32 v76, 16, v72
	v_and_b32_e32 v77, 0xffff0000, v72
	v_lshlrev_b32_e32 v66, 16, v73
	v_and_b32_e32 v67, 0xffff0000, v73
	v_lshlrev_b32_e32 v56, 16, v74
	v_and_b32_e32 v57, 0xffff0000, v74
	v_lshlrev_b32_e32 v48, 16, v75
	v_and_b32_e32 v49, 0xffff0000, v75
	v_lshlrev_b32_e32 v102, 16, v84
	v_and_b32_e32 v103, 0xffff0000, v84
	v_lshlrev_b32_e32 v70, 16, v85
	v_and_b32_e32 v71, 0xffff0000, v85
	v_lshlrev_b32_e32 v84, 16, v80
	v_and_b32_e32 v85, 0xffff0000, v80
	v_lshlrev_b32_e32 v72, 16, v81
	v_and_b32_e32 v73, 0xffff0000, v81
	v_lshlrev_b32_e32 v62, 16, v82
	v_and_b32_e32 v63, 0xffff0000, v82
	v_lshlrev_b32_e32 v52, 16, v83
	v_and_b32_e32 v53, 0xffff0000, v83
	v_lshlrev_b32_e32 v80, 16, v92
	v_and_b32_e32 v81, 0xffff0000, v92
	v_lshlrev_b32_e32 v74, 16, v93
	v_and_b32_e32 v75, 0xffff0000, v93
	v_lshlrev_b32_e32 v82, 16, v88
	v_and_b32_e32 v83, 0xffff0000, v88
	v_lshlrev_b32_e32 v78, 16, v89
	v_and_b32_e32 v79, 0xffff0000, v89
	v_pk_mul_f32 v[88:89], v[86:87], s[8:9] op_sel_hi:[1,0]
	v_pk_mul_f32 v[92:93], v[90:91], s[8:9] op_sel_hi:[1,0]
	v_pk_mul_f32 v[168:169], v[94:95], s[8:9] op_sel_hi:[1,0]
	v_pk_fma_f32 v[170:171], v[22:23], v[128:129], v[170:171]
	v_exp_f32_e32 v88, v88
	v_exp_f32_e32 v89, v89
	v_exp_f32_e32 v92, v92
	v_exp_f32_e32 v93, v93
	v_exp_f32_e32 v168, v168
	v_exp_f32_e32 v169, v169
	v_pk_fma_f32 v[170:171], v[30:31], v[120:121], v[170:171]
	v_pk_add_f32 v[88:89], v[88:89], 1.0 op_sel_hi:[1,0]
	v_pk_mul_f32 v[172:173], v[170:171], s[8:9] op_sel_hi:[1,0]
	v_pk_add_f32 v[92:93], v[92:93], 1.0 op_sel_hi:[1,0]
	v_exp_f32_e32 v172, v172
	v_exp_f32_e32 v173, v173
	v_pk_add_f32 v[168:169], v[168:169], 1.0 op_sel_hi:[1,0]
	v_rcp_f32_e32 v88, v88
	v_rcp_f32_e32 v89, v89
	v_rcp_f32_e32 v92, v92
	v_rcp_f32_e32 v93, v93
	v_rcp_f32_e32 v168, v168
	v_rcp_f32_e32 v169, v169
	v_pk_add_f32 v[172:173], v[172:173], 1.0 op_sel_hi:[1,0]
	v_pk_mul_f32 v[86:87], v[86:87], v[88:89]
	v_rcp_f32_e32 v172, v172
	v_rcp_f32_e32 v173, v173
	v_pk_mul_f32 v[88:89], v[90:91], v[92:93]
	v_pk_mul_f32 v[90:91], v[94:95], v[168:169]
	v_mul_lo_u32 v96, v96, v99
	v_cvt_pk_bf16_f32 v86, v86, v87
	v_cvt_pk_bf16_f32 v87, v88, v89
	v_cvt_pk_bf16_f32 v88, v90, v91
	v_add_u32_e32 v90, v165, v96
	v_pk_mul_f32 v[92:93], v[170:171], v[172:173]
	v_pk_fma_f32 v[94:95], v[32:33], v[146:147], v[36:37]
	v_cvt_pk_bf16_f32 v89, v92, v93
	ds_write_b128 v90, v[86:89]
	v_pk_fma_f32 v[86:87], v[40:41], v[176:177], v[44:45]
	v_pk_fma_f32 v[90:91], v[42:43], v[148:149], v[46:47]
	v_pk_fma_f32 v[86:87], v[0:1], v[142:143], v[86:87]
	v_pk_fma_f32 v[90:91], v[2:3], v[140:141], v[90:91]
	v_pk_fma_f32 v[94:95], v[4:5], v[138:139], v[94:95]
	v_pk_fma_f32 v[86:87], v[8:9], v[134:135], v[86:87]
	v_pk_fma_f32 v[90:91], v[10:11], v[132:133], v[90:91]
	v_pk_fma_f32 v[94:95], v[12:13], v[130:131], v[94:95]
	v_pk_fma_f32 v[144:145], v[34:35], v[144:145], v[38:39]
	v_pk_fma_f32 v[86:87], v[16:17], v[126:127], v[86:87]
	v_pk_fma_f32 v[90:91], v[18:19], v[124:125], v[90:91]
	v_pk_fma_f32 v[94:95], v[20:21], v[122:123], v[94:95]
	v_pk_fma_f32 v[144:145], v[6:7], v[136:137], v[144:145]
	v_pk_fma_f32 v[86:87], v[24:25], v[118:119], v[86:87]
	v_pk_fma_f32 v[90:91], v[26:27], v[116:117], v[90:91]
	v_pk_fma_f32 v[94:95], v[28:29], v[114:115], v[94:95]
	v_pk_fma_f32 v[144:145], v[14:15], v[128:129], v[144:145]
	v_pk_mul_f32 v[88:89], v[86:87], s[8:9] op_sel_hi:[1,0]
	v_pk_mul_f32 v[92:93], v[90:91], s[8:9] op_sel_hi:[1,0]
	v_pk_mul_f32 v[146:147], v[94:95], s[8:9] op_sel_hi:[1,0]
	v_pk_fma_f32 v[144:145], v[22:23], v[120:121], v[144:145]
	v_exp_f32_e32 v88, v88
	v_exp_f32_e32 v89, v89
	v_exp_f32_e32 v92, v92
	v_exp_f32_e32 v93, v93
	v_exp_f32_e32 v146, v146
	v_exp_f32_e32 v147, v147
	v_pk_fma_f32 v[144:145], v[30:31], v[112:113], v[144:145]
	v_pk_add_f32 v[88:89], v[88:89], 1.0 op_sel_hi:[1,0]
	v_pk_mul_f32 v[148:149], v[144:145], s[8:9] op_sel_hi:[1,0]
	v_pk_add_f32 v[92:93], v[92:93], 1.0 op_sel_hi:[1,0]
	v_exp_f32_e32 v148, v148
	v_exp_f32_e32 v149, v149
	v_pk_add_f32 v[146:147], v[146:147], 1.0 op_sel_hi:[1,0]
	v_rcp_f32_e32 v88, v88
	v_rcp_f32_e32 v89, v89
	v_rcp_f32_e32 v92, v92
	v_rcp_f32_e32 v93, v93
	v_rcp_f32_e32 v146, v146
	v_rcp_f32_e32 v147, v147
	v_pk_add_f32 v[148:149], v[148:149], 1.0 op_sel_hi:[1,0]
	v_pk_mul_f32 v[86:87], v[86:87], v[88:89]
	v_rcp_f32_e32 v148, v148
	v_rcp_f32_e32 v149, v149
	v_pk_mul_f32 v[88:89], v[90:91], v[92:93]
	v_pk_mul_f32 v[90:91], v[94:95], v[146:147]
	v_add_u32_e32 v96, v96, v99
	v_cvt_pk_bf16_f32 v86, v86, v87
	v_cvt_pk_bf16_f32 v87, v88, v89
	v_cvt_pk_bf16_f32 v88, v90, v91
	v_add_u32_e32 v90, v165, v96
	v_pk_mul_f32 v[92:93], v[144:145], v[148:149]
	v_pk_fma_f32 v[94:95], v[32:33], v[138:139], v[36:37]
	v_cvt_pk_bf16_f32 v89, v92, v93
	ds_write_b128 v90, v[86:89]
	v_pk_fma_f32 v[86:87], v[40:41], v[142:143], v[44:45]
	v_pk_fma_f32 v[90:91], v[42:43], v[140:141], v[46:47]
	v_pk_fma_f32 v[86:87], v[0:1], v[134:135], v[86:87]
	v_pk_fma_f32 v[90:91], v[2:3], v[132:133], v[90:91]
	v_pk_fma_f32 v[94:95], v[4:5], v[130:131], v[94:95]
	v_pk_fma_f32 v[86:87], v[8:9], v[126:127], v[86:87]
	v_pk_fma_f32 v[90:91], v[10:11], v[124:125], v[90:91]
	v_pk_fma_f32 v[94:95], v[12:13], v[122:123], v[94:95]
	v_pk_fma_f32 v[136:137], v[34:35], v[136:137], v[38:39]
	v_pk_fma_f32 v[86:87], v[16:17], v[118:119], v[86:87]
	v_pk_fma_f32 v[90:91], v[18:19], v[116:117], v[90:91]
	v_pk_fma_f32 v[94:95], v[20:21], v[114:115], v[94:95]
	v_pk_fma_f32 v[136:137], v[6:7], v[128:129], v[136:137]
	v_pk_fma_f32 v[86:87], v[24:25], v[110:111], v[86:87]
	v_pk_fma_f32 v[90:91], v[26:27], v[108:109], v[90:91]
	v_pk_fma_f32 v[94:95], v[28:29], v[106:107], v[94:95]
	v_pk_fma_f32 v[136:137], v[14:15], v[120:121], v[136:137]
	v_pk_mul_f32 v[88:89], v[86:87], s[8:9] op_sel_hi:[1,0]
	v_pk_mul_f32 v[92:93], v[90:91], s[8:9] op_sel_hi:[1,0]
	v_pk_mul_f32 v[138:139], v[94:95], s[8:9] op_sel_hi:[1,0]
	v_pk_fma_f32 v[136:137], v[22:23], v[112:113], v[136:137]
	v_exp_f32_e32 v88, v88
	v_exp_f32_e32 v89, v89
	v_exp_f32_e32 v92, v92
	v_exp_f32_e32 v93, v93
	v_exp_f32_e32 v138, v138
	v_exp_f32_e32 v139, v139
	v_pk_fma_f32 v[136:137], v[30:31], v[104:105], v[136:137]
	v_pk_add_f32 v[88:89], v[88:89], 1.0 op_sel_hi:[1,0]
	v_pk_mul_f32 v[140:141], v[136:137], s[8:9] op_sel_hi:[1,0]
	v_pk_add_f32 v[92:93], v[92:93], 1.0 op_sel_hi:[1,0]
	v_exp_f32_e32 v140, v140
	v_exp_f32_e32 v141, v141
	v_pk_add_f32 v[138:139], v[138:139], 1.0 op_sel_hi:[1,0]
	v_rcp_f32_e32 v88, v88
	v_rcp_f32_e32 v89, v89
	v_rcp_f32_e32 v92, v92
	v_rcp_f32_e32 v93, v93
	v_rcp_f32_e32 v138, v138
	v_rcp_f32_e32 v139, v139
	v_pk_add_f32 v[140:141], v[140:141], 1.0 op_sel_hi:[1,0]
	v_pk_mul_f32 v[86:87], v[86:87], v[88:89]
	v_rcp_f32_e32 v140, v140
	v_rcp_f32_e32 v141, v141
	v_pk_mul_f32 v[88:89], v[90:91], v[92:93]
	v_pk_mul_f32 v[90:91], v[94:95], v[138:139]
	v_add_u32_e32 v96, v96, v99
	v_cvt_pk_bf16_f32 v86, v86, v87
	v_cvt_pk_bf16_f32 v87, v88, v89
	v_cvt_pk_bf16_f32 v88, v90, v91
	v_add_u32_e32 v90, v165, v96
	v_pk_mul_f32 v[92:93], v[136:137], v[140:141]
	v_pk_fma_f32 v[94:95], v[32:33], v[130:131], v[36:37]
	v_cvt_pk_bf16_f32 v89, v92, v93
	ds_write_b128 v90, v[86:89]
	v_pk_fma_f32 v[86:87], v[40:41], v[134:135], v[44:45]
	v_pk_fma_f32 v[90:91], v[42:43], v[132:133], v[46:47]
	v_pk_fma_f32 v[86:87], v[0:1], v[126:127], v[86:87]
	v_pk_fma_f32 v[90:91], v[2:3], v[124:125], v[90:91]
	v_pk_fma_f32 v[94:95], v[4:5], v[122:123], v[94:95]
	v_pk_fma_f32 v[86:87], v[8:9], v[118:119], v[86:87]
	v_pk_fma_f32 v[90:91], v[10:11], v[116:117], v[90:91]
	v_pk_fma_f32 v[94:95], v[12:13], v[114:115], v[94:95]
	v_pk_fma_f32 v[128:129], v[34:35], v[128:129], v[38:39]
	v_pk_fma_f32 v[86:87], v[16:17], v[110:111], v[86:87]
	v_pk_fma_f32 v[90:91], v[18:19], v[108:109], v[90:91]
	v_pk_fma_f32 v[94:95], v[20:21], v[106:107], v[94:95]
	v_pk_fma_f32 v[128:129], v[6:7], v[120:121], v[128:129]
	v_pk_fma_f32 v[86:87], v[24:25], v[76:77], v[86:87]
	v_pk_fma_f32 v[90:91], v[26:27], v[66:67], v[90:91]
	v_pk_fma_f32 v[94:95], v[28:29], v[56:57], v[94:95]
	v_pk_fma_f32 v[128:129], v[14:15], v[112:113], v[128:129]
	v_pk_mul_f32 v[88:89], v[86:87], s[8:9] op_sel_hi:[1,0]
	v_pk_mul_f32 v[92:93], v[90:91], s[8:9] op_sel_hi:[1,0]
	v_pk_mul_f32 v[130:131], v[94:95], s[8:9] op_sel_hi:[1,0]
	v_pk_fma_f32 v[128:129], v[22:23], v[104:105], v[128:129]
	v_exp_f32_e32 v88, v88
	v_exp_f32_e32 v89, v89
	v_exp_f32_e32 v92, v92
	v_exp_f32_e32 v93, v93
	v_exp_f32_e32 v130, v130
	v_exp_f32_e32 v131, v131
	v_pk_fma_f32 v[128:129], v[30:31], v[48:49], v[128:129]
	v_pk_add_f32 v[88:89], v[88:89], 1.0 op_sel_hi:[1,0]
	v_pk_mul_f32 v[132:133], v[128:129], s[8:9] op_sel_hi:[1,0]
	v_pk_add_f32 v[92:93], v[92:93], 1.0 op_sel_hi:[1,0]
	v_exp_f32_e32 v132, v132
	v_exp_f32_e32 v133, v133
	v_pk_add_f32 v[130:131], v[130:131], 1.0 op_sel_hi:[1,0]
	v_rcp_f32_e32 v88, v88
	v_rcp_f32_e32 v89, v89
	v_rcp_f32_e32 v92, v92
	v_rcp_f32_e32 v93, v93
	v_rcp_f32_e32 v130, v130
	v_rcp_f32_e32 v131, v131
	v_pk_add_f32 v[132:133], v[132:133], 1.0 op_sel_hi:[1,0]
	v_pk_mul_f32 v[86:87], v[86:87], v[88:89]
	v_rcp_f32_e32 v132, v132
	v_rcp_f32_e32 v133, v133
	v_pk_mul_f32 v[88:89], v[90:91], v[92:93]
	v_pk_mul_f32 v[90:91], v[94:95], v[130:131]
	v_add_u32_e32 v96, v96, v99
	v_cvt_pk_bf16_f32 v86, v86, v87
	v_cvt_pk_bf16_f32 v87, v88, v89
	v_cvt_pk_bf16_f32 v88, v90, v91
	v_add_u32_e32 v90, v165, v96
	v_pk_mul_f32 v[92:93], v[128:129], v[132:133]
	v_pk_fma_f32 v[94:95], v[32:33], v[122:123], v[36:37]
	v_cvt_pk_bf16_f32 v89, v92, v93
	ds_write_b128 v90, v[86:89]
	v_pk_fma_f32 v[86:87], v[40:41], v[126:127], v[44:45]
	v_pk_fma_f32 v[90:91], v[42:43], v[124:125], v[46:47]
	v_pk_fma_f32 v[86:87], v[0:1], v[118:119], v[86:87]
	v_pk_fma_f32 v[90:91], v[2:3], v[116:117], v[90:91]
	v_pk_fma_f32 v[94:95], v[4:5], v[114:115], v[94:95]
	v_pk_fma_f32 v[86:87], v[8:9], v[110:111], v[86:87]
	v_pk_fma_f32 v[90:91], v[10:11], v[108:109], v[90:91]
	v_pk_fma_f32 v[94:95], v[12:13], v[106:107], v[94:95]
	v_pk_fma_f32 v[120:121], v[34:35], v[120:121], v[38:39]
	v_pk_fma_f32 v[86:87], v[16:17], v[76:77], v[86:87]
	v_pk_fma_f32 v[90:91], v[18:19], v[66:67], v[90:91]
	v_pk_fma_f32 v[94:95], v[20:21], v[56:57], v[94:95]
	v_pk_fma_f32 v[120:121], v[6:7], v[112:113], v[120:121]
	v_pk_fma_f32 v[86:87], v[24:25], v[102:103], v[86:87]
	v_pk_fma_f32 v[90:91], v[26:27], v[70:71], v[90:91]
	v_pk_fma_f32 v[94:95], v[28:29], v[60:61], v[94:95]
	v_pk_fma_f32 v[120:121], v[14:15], v[104:105], v[120:121]
	v_pk_mul_f32 v[88:89], v[86:87], s[8:9] op_sel_hi:[1,0]
	v_pk_mul_f32 v[92:93], v[90:91], s[8:9] op_sel_hi:[1,0]
	v_pk_mul_f32 v[122:123], v[94:95], s[8:9] op_sel_hi:[1,0]
	v_pk_fma_f32 v[120:121], v[22:23], v[48:49], v[120:121]
	v_exp_f32_e32 v88, v88
	v_exp_f32_e32 v89, v89
	v_exp_f32_e32 v92, v92
	v_exp_f32_e32 v93, v93
	v_exp_f32_e32 v122, v122
	v_exp_f32_e32 v123, v123
	v_pk_fma_f32 v[120:121], v[30:31], v[50:51], v[120:121]
	v_pk_add_f32 v[88:89], v[88:89], 1.0 op_sel_hi:[1,0]
	v_pk_mul_f32 v[124:125], v[120:121], s[8:9] op_sel_hi:[1,0]
	v_pk_add_f32 v[92:93], v[92:93], 1.0 op_sel_hi:[1,0]
	v_exp_f32_e32 v124, v124
	v_exp_f32_e32 v125, v125
	v_pk_add_f32 v[122:123], v[122:123], 1.0 op_sel_hi:[1,0]
	v_rcp_f32_e32 v88, v88
	v_rcp_f32_e32 v89, v89
	v_rcp_f32_e32 v92, v92
	v_rcp_f32_e32 v93, v93
	v_rcp_f32_e32 v122, v122
	v_rcp_f32_e32 v123, v123
	v_pk_add_f32 v[124:125], v[124:125], 1.0 op_sel_hi:[1,0]
	v_pk_mul_f32 v[86:87], v[86:87], v[88:89]
	v_rcp_f32_e32 v124, v124
	v_rcp_f32_e32 v125, v125
	v_pk_mul_f32 v[88:89], v[90:91], v[92:93]
	v_pk_mul_f32 v[90:91], v[94:95], v[122:123]
	v_add_u32_e32 v96, v96, v99
	v_cvt_pk_bf16_f32 v86, v86, v87
	v_cvt_pk_bf16_f32 v87, v88, v89
	v_cvt_pk_bf16_f32 v88, v90, v91
	v_add_u32_e32 v90, v165, v96
	v_pk_mul_f32 v[92:93], v[120:121], v[124:125]
	v_pk_fma_f32 v[94:95], v[32:33], v[114:115], v[36:37]
	v_cvt_pk_bf16_f32 v89, v92, v93
	ds_write_b128 v90, v[86:89]
	v_pk_fma_f32 v[86:87], v[40:41], v[118:119], v[44:45]
	v_pk_fma_f32 v[90:91], v[42:43], v[116:117], v[46:47]
	v_pk_fma_f32 v[86:87], v[0:1], v[110:111], v[86:87]
	v_pk_fma_f32 v[90:91], v[2:3], v[108:109], v[90:91]
	v_pk_fma_f32 v[94:95], v[4:5], v[106:107], v[94:95]
	v_pk_fma_f32 v[86:87], v[8:9], v[76:77], v[86:87]
	v_pk_fma_f32 v[90:91], v[10:11], v[66:67], v[90:91]
	v_pk_fma_f32 v[94:95], v[12:13], v[56:57], v[94:95]
	v_pk_fma_f32 v[112:113], v[34:35], v[112:113], v[38:39]
	v_pk_fma_f32 v[86:87], v[16:17], v[102:103], v[86:87]
	v_pk_fma_f32 v[90:91], v[18:19], v[70:71], v[90:91]
	v_pk_fma_f32 v[94:95], v[20:21], v[60:61], v[94:95]
	v_pk_fma_f32 v[112:113], v[6:7], v[104:105], v[112:113]
	v_pk_fma_f32 v[86:87], v[24:25], v[84:85], v[86:87]
	v_pk_fma_f32 v[90:91], v[26:27], v[72:73], v[90:91]
	v_pk_fma_f32 v[94:95], v[28:29], v[62:63], v[94:95]
	v_pk_fma_f32 v[112:113], v[14:15], v[48:49], v[112:113]
	v_pk_mul_f32 v[88:89], v[86:87], s[8:9] op_sel_hi:[1,0]
	v_pk_mul_f32 v[92:93], v[90:91], s[8:9] op_sel_hi:[1,0]
	v_pk_mul_f32 v[114:115], v[94:95], s[8:9] op_sel_hi:[1,0]
	v_pk_fma_f32 v[112:113], v[22:23], v[50:51], v[112:113]
	v_exp_f32_e32 v88, v88
	v_exp_f32_e32 v89, v89
	v_exp_f32_e32 v92, v92
	v_exp_f32_e32 v93, v93
	v_exp_f32_e32 v114, v114
	v_exp_f32_e32 v115, v115
	v_pk_fma_f32 v[112:113], v[30:31], v[52:53], v[112:113]
	v_pk_add_f32 v[88:89], v[88:89], 1.0 op_sel_hi:[1,0]
	v_pk_mul_f32 v[116:117], v[112:113], s[8:9] op_sel_hi:[1,0]
	v_pk_add_f32 v[92:93], v[92:93], 1.0 op_sel_hi:[1,0]
	v_exp_f32_e32 v116, v116
	v_exp_f32_e32 v117, v117
	v_pk_add_f32 v[114:115], v[114:115], 1.0 op_sel_hi:[1,0]
	v_rcp_f32_e32 v88, v88
	v_rcp_f32_e32 v89, v89
	v_rcp_f32_e32 v92, v92
	v_rcp_f32_e32 v93, v93
	v_rcp_f32_e32 v114, v114
	v_rcp_f32_e32 v115, v115
	v_pk_add_f32 v[116:117], v[116:117], 1.0 op_sel_hi:[1,0]
	v_pk_mul_f32 v[86:87], v[86:87], v[88:89]
	v_rcp_f32_e32 v116, v116
	v_rcp_f32_e32 v117, v117
	v_pk_mul_f32 v[88:89], v[90:91], v[92:93]
	v_pk_mul_f32 v[90:91], v[94:95], v[114:115]
	v_add_u32_e32 v96, v96, v99
	v_cvt_pk_bf16_f32 v86, v86, v87
	v_cvt_pk_bf16_f32 v87, v88, v89
	v_cvt_pk_bf16_f32 v88, v90, v91
	v_add_u32_e32 v90, v165, v96
	v_pk_mul_f32 v[92:93], v[112:113], v[116:117]
	v_pk_fma_f32 v[94:95], v[32:33], v[106:107], v[36:37]
	v_cvt_pk_bf16_f32 v89, v92, v93
	ds_write_b128 v90, v[86:89]
	v_pk_fma_f32 v[86:87], v[40:41], v[110:111], v[44:45]
	v_pk_fma_f32 v[90:91], v[42:43], v[108:109], v[46:47]
	v_pk_fma_f32 v[86:87], v[0:1], v[76:77], v[86:87]
	v_pk_fma_f32 v[90:91], v[2:3], v[66:67], v[90:91]
	v_pk_fma_f32 v[94:95], v[4:5], v[56:57], v[94:95]
	v_pk_fma_f32 v[86:87], v[8:9], v[102:103], v[86:87]
	v_pk_fma_f32 v[90:91], v[10:11], v[70:71], v[90:91]
	v_pk_fma_f32 v[94:95], v[12:13], v[60:61], v[94:95]
	v_pk_fma_f32 v[104:105], v[34:35], v[104:105], v[38:39]
	v_pk_fma_f32 v[56:57], v[32:33], v[56:57], v[36:37]
	v_pk_fma_f32 v[86:87], v[16:17], v[84:85], v[86:87]
	v_pk_fma_f32 v[90:91], v[18:19], v[72:73], v[90:91]
	v_pk_fma_f32 v[94:95], v[20:21], v[62:63], v[94:95]
	v_pk_fma_f32 v[104:105], v[6:7], v[48:49], v[104:105]
	v_pk_fma_f32 v[76:77], v[40:41], v[76:77], v[44:45]
	v_pk_fma_f32 v[66:67], v[42:43], v[66:67], v[46:47]
	v_pk_fma_f32 v[56:57], v[4:5], v[60:61], v[56:57]
	v_pk_fma_f32 v[48:49], v[34:35], v[48:49], v[38:39]
	v_pk_fma_f32 v[86:87], v[24:25], v[80:81], v[86:87]
	v_pk_fma_f32 v[90:91], v[26:27], v[74:75], v[90:91]
	v_pk_fma_f32 v[94:95], v[28:29], v[64:65], v[94:95]
	v_pk_fma_f32 v[76:77], v[0:1], v[102:103], v[76:77]
	v_pk_fma_f32 v[66:67], v[2:3], v[70:71], v[66:67]
	v_pk_fma_f32 v[56:57], v[12:13], v[62:63], v[56:57]
	v_pk_fma_f32 v[48:49], v[6:7], v[50:51], v[48:49]
	v_pk_mul_f32 v[88:89], v[86:87], s[8:9] op_sel_hi:[1,0]
	v_pk_mul_f32 v[92:93], v[90:91], s[8:9] op_sel_hi:[1,0]
	v_pk_mul_f32 v[106:107], v[94:95], s[8:9] op_sel_hi:[1,0]
	v_pk_fma_f32 v[104:105], v[14:15], v[50:51], v[104:105]
	v_pk_fma_f32 v[76:77], v[8:9], v[84:85], v[76:77]
	v_pk_fma_f32 v[66:67], v[10:11], v[72:73], v[66:67]
	v_pk_fma_f32 v[56:57], v[20:21], v[64:65], v[56:57]
	v_pk_fma_f32 v[48:49], v[14:15], v[52:53], v[48:49]
	v_exp_f32_e32 v88, v88
	v_exp_f32_e32 v89, v89
	v_exp_f32_e32 v92, v92
	v_exp_f32_e32 v93, v93
	v_exp_f32_e32 v106, v106
	v_exp_f32_e32 v107, v107
	v_pk_fma_f32 v[104:105], v[22:23], v[52:53], v[104:105]
	v_pk_fma_f32 v[76:77], v[16:17], v[80:81], v[76:77]
	v_pk_fma_f32 v[66:67], v[18:19], v[74:75], v[66:67]
	v_pk_fma_f32 v[56:57], v[28:29], v[68:69], v[56:57]
	v_pk_fma_f32 v[48:49], v[22:23], v[54:55], v[48:49]
	v_pk_fma_f32 v[104:105], v[30:31], v[54:55], v[104:105]
	v_pk_fma_f32 v[76:77], v[24:25], v[82:83], v[76:77]
	v_pk_fma_f32 v[66:67], v[26:27], v[78:79], v[66:67]
	v_pk_mul_f32 v[60:61], v[56:57], s[8:9] op_sel_hi:[1,0]
	v_pk_fma_f32 v[48:49], v[30:31], v[58:59], v[48:49]
	v_pk_mul_f32 v[108:109], v[104:105], s[8:9] op_sel_hi:[1,0]
	v_pk_mul_f32 v[80:81], v[76:77], s[8:9] op_sel_hi:[1,0]
	v_pk_mul_f32 v[70:71], v[66:67], s[8:9] op_sel_hi:[1,0]
	v_exp_f32_e32 v60, v60
	v_exp_f32_e32 v61, v61
	v_pk_mul_f32 v[50:51], v[48:49], s[8:9] op_sel_hi:[1,0]
	v_exp_f32_e32 v108, v108
	v_exp_f32_e32 v109, v109
	v_exp_f32_e32 v80, v80
	v_exp_f32_e32 v81, v81
	v_exp_f32_e32 v70, v70
	v_exp_f32_e32 v71, v71
	v_exp_f32_e32 v50, v50
	v_exp_f32_e32 v51, v51
	v_pk_add_f32 v[88:89], v[88:89], 1.0 op_sel_hi:[1,0]
	v_pk_add_f32 v[92:93], v[92:93], 1.0 op_sel_hi:[1,0]
	v_pk_add_f32 v[106:107], v[106:107], 1.0 op_sel_hi:[1,0]
	v_rcp_f32_e32 v88, v88
	v_rcp_f32_e32 v89, v89
	v_rcp_f32_e32 v92, v92
	v_rcp_f32_e32 v93, v93
	v_rcp_f32_e32 v106, v106
	v_rcp_f32_e32 v107, v107
	v_pk_add_f32 v[52:53], v[60:61], 1.0 op_sel_hi:[1,0]
	v_pk_add_f32 v[108:109], v[108:109], 1.0 op_sel_hi:[1,0]
	v_pk_add_f32 v[72:73], v[80:81], 1.0 op_sel_hi:[1,0]
	v_pk_add_f32 v[70:71], v[70:71], 1.0 op_sel_hi:[1,0]
	v_rcp_f32_e32 v52, v52
	v_rcp_f32_e32 v53, v53
	v_pk_add_f32 v[50:51], v[50:51], 1.0 op_sel_hi:[1,0]
	v_rcp_f32_e32 v108, v108
	v_rcp_f32_e32 v109, v109
	v_rcp_f32_e32 v72, v72
	v_rcp_f32_e32 v73, v73
	v_rcp_f32_e32 v70, v70
	v_rcp_f32_e32 v71, v71
	v_rcp_f32_e32 v50, v50
	v_rcp_f32_e32 v51, v51
	v_pk_mul_f32 v[86:87], v[86:87], v[88:89]
	v_pk_mul_f32 v[88:89], v[90:91], v[92:93]
	v_pk_mul_f32 v[90:91], v[94:95], v[106:107]
	v_cvt_pk_bf16_f32 v86, v86, v87
	v_cvt_pk_bf16_f32 v87, v88, v89
	s_xor_b64 s[0:1], s[16:17], -1
	v_cvt_pk_bf16_f32 v88, v90, v91
	v_add_u32_e32 v90, v96, v99
	v_add_u32_e32 v91, v165, v90
	v_pk_mul_f32 v[52:53], v[56:57], v[52:53]
	v_pk_mul_f32 v[92:93], v[104:105], v[108:109]
	v_pk_mul_f32 v[54:55], v[76:77], v[72:73]
	v_cvt_pk_bf16_f32 v89, v92, v93
	ds_write_b128 v91, v[86:89]
	v_pk_mul_f32 v[58:59], v[66:67], v[70:71]
	v_pk_mul_f32 v[56:57], v[48:49], v[50:51]
	v_cvt_pk_bf16_f32 v48, v54, v55
	v_cvt_pk_bf16_f32 v49, v58, v59
	v_cvt_pk_bf16_f32 v50, v52, v53
	v_add3_u32 v52, v90, v99, v165
	s_mov_b32 s47, 8
	s_andn2_b64 vcc, exec, s[0:1]
	s_mov_b64 s[16:17], 0
	v_cvt_pk_bf16_f32 v51, v56, v57
	ds_write_b128 v52, v[48:51]
	s_cbranch_vccz .LBB0_677
.Lcv3_second:
	s_waitcnt vmcnt(0)
	v_readfirstlane_b32 s100, v166
	s_nop 0
	s_add_i32 s100, s100, s46
	s_add_i32 s100, s100, 8
	s_cmp_lt_i32 s100, s45
	s_cselect_b64 vcc, -1, 0
	s_add_i32 s100, s100, 1
	v_cndmask_b32_e32 v52, 0, v200, vcc
	v_cndmask_b32_e32 v53, 0, v201, vcc
	v_cndmask_b32_e32 v54, 0, v202, vcc
	v_cndmask_b32_e32 v55, 0, v203, vcc
	s_cmp_lt_i32 s100, s45
	s_cselect_b64 vcc, -1, 0
	s_add_i32 s100, s100, 1
	v_cndmask_b32_e32 v48, 0, v204, vcc
	v_cndmask_b32_e32 v49, 0, v205, vcc
	v_cndmask_b32_e32 v50, 0, v206, vcc
	v_cndmask_b32_e32 v51, 0, v207, vcc
	s_cmp_lt_i32 s100, s45
	s_cselect_b64 vcc, -1, 0
	s_add_i32 s100, s100, 1
	v_cndmask_b32_e32 v60, 0, v208, vcc
	v_cndmask_b32_e32 v61, 0, v209, vcc
	v_cndmask_b32_e32 v62, 0, v210, vcc
	v_cndmask_b32_e32 v63, 0, v211, vcc
	s_cmp_lt_i32 s100, s45
	s_cselect_b64 vcc, -1, 0
	s_add_i32 s100, s100, 1
	v_cndmask_b32_e32 v56, 0, v212, vcc
	v_cndmask_b32_e32 v57, 0, v213, vcc
	v_cndmask_b32_e32 v58, 0, v214, vcc
	v_cndmask_b32_e32 v59, 0, v215, vcc
	s_cmp_lt_i32 s100, s45
	s_cselect_b64 vcc, -1, 0
	s_add_i32 s100, s100, 1
	v_cndmask_b32_e32 v68, 0, v216, vcc
	v_cndmask_b32_e32 v69, 0, v217, vcc
	v_cndmask_b32_e32 v70, 0, v218, vcc
	v_cndmask_b32_e32 v71, 0, v219, vcc
	s_cmp_lt_i32 s100, s45
	s_cselect_b64 vcc, -1, 0
	s_add_i32 s100, s100, 1
	v_cndmask_b32_e32 v64, 0, v220, vcc
	v_cndmask_b32_e32 v65, 0, v221, vcc
	v_cndmask_b32_e32 v66, 0, v222, vcc
	v_cndmask_b32_e32 v67, 0, v223, vcc
	s_cmp_lt_i32 s100, s45
	s_cselect_b64 vcc, -1, 0
	s_add_i32 s100, s100, 1
	v_cndmask_b32_e32 v76, 0, v224, vcc
	v_cndmask_b32_e32 v77, 0, v225, vcc
	v_cndmask_b32_e32 v78, 0, v226, vcc
	v_cndmask_b32_e32 v79, 0, v227, vcc
	s_cmp_lt_i32 s100, s45
	s_cselect_b64 vcc, -1, 0
	s_add_i32 s100, s100, 1
	v_cndmask_b32_e32 v72, 0, v228, vcc
	v_cndmask_b32_e32 v73, 0, v229, vcc
	v_cndmask_b32_e32 v74, 0, v230, vcc
	v_cndmask_b32_e32 v75, 0, v231, vcc
	s_cmp_lt_i32 s100, s45
	s_cselect_b64 vcc, -1, 0
	s_add_i32 s100, s100, 1
	v_cndmask_b32_e32 v84, 0, v232, vcc
	v_cndmask_b32_e32 v85, 0, v233, vcc
	v_cndmask_b32_e32 v86, 0, v234, vcc
	v_cndmask_b32_e32 v87, 0, v235, vcc
	s_cmp_lt_i32 s100, s45
	s_cselect_b64 vcc, -1, 0
	s_add_i32 s100, s100, 1
	v_cndmask_b32_e32 v80, 0, v236, vcc
	v_cndmask_b32_e32 v81, 0, v237, vcc
	v_cndmask_b32_e32 v82, 0, v238, vcc
	v_cndmask_b32_e32 v83, 0, v239, vcc
	s_cmp_lt_i32 s100, s45
	s_cselect_b64 vcc, -1, 0
	s_add_i32 s100, s100, 1
	v_cndmask_b32_e32 v92, 0, v240, vcc
	v_cndmask_b32_e32 v93, 0, v241, vcc
	v_cndmask_b32_e32 v94, 0, v242, vcc
	v_cndmask_b32_e32 v95, 0, v243, vcc
	s_cmp_lt_i32 s100, s45
	s_cselect_b64 vcc, -1, 0
	s_add_i32 s100, s100, 1
	v_cndmask_b32_e32 v88, 0, v244, vcc
	v_cndmask_b32_e32 v89, 0, v245, vcc
	v_cndmask_b32_e32 v90, 0, v246, vcc
	v_cndmask_b32_e32 v91, 0, v247, vcc
	v_or_b32_e32 v96, 8, v166
	s_branch .Lcv3_go

.LBB0_825:
	s_or_b64 exec, exec, s[0:1]
	s_waitcnt vmcnt(0)
	v_add_u32_e32 v252, s9, v144
	v_add_u32_e32 v250, 8, v252
	v_min_i32_e32 v250, 0x4fff, v250
	v_mov_b32_e32 v251, 0
	v_lshlrev_b64 v[250:251], 12, v[250:251]
	v_lshl_add_u64 v[250:251], v[96:97], 0, v[250:251]
	global_load_dwordx4 v[208:211], v[250:251], off
	v_add_u32_e32 v250, 9, v252
	v_min_i32_e32 v250, 0x4fff, v250
	v_mov_b32_e32 v251, 0
	v_lshlrev_b64 v[250:251], 12, v[250:251]
	v_lshl_add_u64 v[250:251], v[96:97], 0, v[250:251]
	global_load_dwordx4 v[212:215], v[250:251], off
	v_add_u32_e32 v250, 10, v252
	v_min_i32_e32 v250, 0x4fff, v250
	v_mov_b32_e32 v251, 0
	v_lshlrev_b64 v[250:251], 12, v[250:251]
	v_lshl_add_u64 v[250:251], v[96:97], 0, v[250:251]
	global_load_dwordx4 v[216:219], v[250:251], off
	v_add_u32_e32 v250, 11, v252
	v_min_i32_e32 v250, 0x4fff, v250
	v_mov_b32_e32 v251, 0
	v_lshlrev_b64 v[250:251], 12, v[250:251]
	v_lshl_add_u64 v[250:251], v[96:97], 0, v[250:251]
	global_load_dwordx4 v[220:223], v[250:251], off
	v_add_u32_e32 v250, 12, v252
	v_min_i32_e32 v250, 0x4fff, v250
	v_mov_b32_e32 v251, 0
	v_lshlrev_b64 v[250:251], 12, v[250:251]
	v_lshl_add_u64 v[250:251], v[96:97], 0, v[250:251]
	global_load_dwordx4 v[224:227], v[250:251], off
	v_add_u32_e32 v250, 13, v252
	v_min_i32_e32 v250, 0x4fff, v250
	v_mov_b32_e32 v251, 0
	v_lshlrev_b64 v[250:251], 12, v[250:251]
	v_lshl_add_u64 v[250:251], v[96:97], 0, v[250:251]
	global_load_dwordx4 v[228:231], v[250:251], off
	v_add_u32_e32 v250, 14, v252
	v_min_i32_e32 v250, 0x4fff, v250
	v_mov_b32_e32 v251, 0
	v_lshlrev_b64 v[250:251], 12, v[250:251]
	v_lshl_add_u64 v[250:251], v[96:97], 0, v[250:251]
	global_load_dwordx4 v[232:235], v[250:251], off
	v_add_u32_e32 v250, 15, v252
	v_min_i32_e32 v250, 0x4fff, v250
	v_mov_b32_e32 v251, 0
	v_lshlrev_b64 v[250:251], 12, v[250:251]
	v_lshl_add_u64 v[250:251], v[96:97], 0, v[250:251]
	global_load_dwordx4 v[236:239], v[250:251], off
	v_add_u32_e32 v250, 16, v252
	v_min_i32_e32 v250, 0x4fff, v250
	v_mov_b32_e32 v251, 0
	v_lshlrev_b64 v[250:251], 12, v[250:251]
	v_lshl_add_u64 v[250:251], v[96:97], 0, v[250:251]
	global_load_dwordx4 v[240:243], v[250:251], off
	v_add_u32_e32 v250, 17, v252
	v_min_i32_e32 v250, 0x4fff, v250
	v_mov_b32_e32 v251, 0
	v_lshlrev_b64 v[250:251], 12, v[250:251]
	v_lshl_add_u64 v[250:251], v[96:97], 0, v[250:251]
	global_load_dwordx4 v[244:247], v[250:251], off
	v_add_u32_e32 v250, 18, v252
	v_min_i32_e32 v250, 0x4fff, v250
	v_mov_b32_e32 v251, 0
	v_lshlrev_b64 v[250:251], 12, v[250:251]
	v_lshl_add_u64 v[250:251], v[96:97], 0, v[250:251]
	global_load_dwordx4 v[162:165], v[250:251], off
	v_add_u32_e32 v250, 19, v252
	v_min_i32_e32 v250, 0x4fff, v250
	v_mov_b32_e32 v251, 0
	v_lshlrev_b64 v[250:251], 12, v[250:251]
	v_lshl_add_u64 v[250:251], v[96:97], 0, v[250:251]
	global_load_dwordx4 v[166:169], v[250:251], off
.Lcv5_go:
	v_lshlrev_b32_e32 v146, 16, v52
	v_and_b32_e32 v147, 0xffff0000, v52
	v_lshlrev_b32_e32 v148, 16, v53
	v_and_b32_e32 v149, 0xffff0000, v53
	v_lshlrev_b32_e32 v150, 16, v54
	v_and_b32_e32 v151, 0xffff0000, v54
	v_lshlrev_b32_e32 v152, 16, v55
	v_and_b32_e32 v153, 0xffff0000, v55
	v_lshlrev_b32_e32 v154, 16, v48
	v_and_b32_e32 v155, 0xffff0000, v48
	v_lshlrev_b32_e32 v156, 16, v49
	v_and_b32_e32 v157, 0xffff0000, v49
	v_lshlrev_b32_e32 v140, 16, v50
	v_and_b32_e32 v141, 0xffff0000, v50
	v_lshlrev_b32_e32 v138, 16, v51
	v_and_b32_e32 v139, 0xffff0000, v51
	v_lshlrev_b32_e32 v132, 16, v62
	v_and_b32_e32 v133, 0xffff0000, v62
	v_lshlrev_b32_e32 v130, 16, v63
	v_and_b32_e32 v131, 0xffff0000, v63
	v_lshlrev_b32_e32 v124, 16, v58
	v_and_b32_e32 v125, 0xffff0000, v58
	v_lshlrev_b32_e32 v122, 16, v59
	v_and_b32_e32 v123, 0xffff0000, v59
	v_lshlrev_b32_e32 v116, 16, v70
	v_and_b32_e32 v117, 0xffff0000, v70
	v_lshlrev_b32_e32 v114, 16, v71
	v_and_b32_e32 v115, 0xffff0000, v71
	v_lshlrev_b32_e32 v108, 16, v66
	v_and_b32_e32 v109, 0xffff0000, v66
	v_lshlrev_b32_e32 v106, 16, v67
	v_and_b32_e32 v107, 0xffff0000, v67
	v_lshlrev_b32_e32 v104, 16, v76
	v_and_b32_e32 v105, 0xffff0000, v76
	v_lshlrev_b32_e32 v102, 16, v77
	v_and_b32_e32 v103, 0xffff0000, v77
	v_lshlrev_b32_e32 v100, 16, v78
	v_and_b32_e32 v101, 0xffff0000, v78
	v_lshlrev_b32_e32 v98, 16, v79
	v_and_b32_e32 v99, 0xffff0000, v79
	v_lshlrev_b32_e32 v76, 16, v72
	v_and_b32_e32 v77, 0xffff0000, v72
	v_lshlrev_b32_e32 v66, 16, v73
	v_and_b32_e32 v67, 0xffff0000, v73
	v_lshlrev_b32_e32 v54, 16, v74
	v_and_b32_e32 v55, 0xffff0000, v74
	v_lshlrev_b32_e32 v48, 16, v75
	v_and_b32_e32 v49, 0xffff0000, v75
	v_lshlrev_b32_e32 v78, 16, v84
	v_and_b32_e32 v79, 0xffff0000, v84
	v_lshlrev_b32_e32 v70, 16, v85
	v_and_b32_e32 v71, 0xffff0000, v85
	v_lshlrev_b32_e32 v58, 16, v86
	v_and_b32_e32 v59, 0xffff0000, v86
	v_lshlrev_b32_e32 v50, 16, v87
	v_and_b32_e32 v51, 0xffff0000, v87
	v_lshlrev_b32_e32 v84, 16, v80
	v_and_b32_e32 v85, 0xffff0000, v80
	v_lshlrev_b32_e32 v72, 16, v81
	v_and_b32_e32 v73, 0xffff0000, v81
	v_lshlrev_b32_e32 v62, 16, v82
	v_and_b32_e32 v63, 0xffff0000, v82
	v_lshlrev_b32_e32 v52, 16, v83
	v_and_b32_e32 v53, 0xffff0000, v83
	v_lshlrev_b32_e32 v82, 16, v92
	v_and_b32_e32 v83, 0xffff0000, v92
	v_lshlrev_b32_e32 v74, 16, v93
	v_and_b32_e32 v75, 0xffff0000, v93
	v_lshlrev_b32_e32 v86, 16, v88
	v_and_b32_e32 v87, 0xffff0000, v88
	v_lshlrev_b32_e32 v80, 16, v89
	v_and_b32_e32 v81, 0xffff0000, v89
	v_pk_fma_f32 v[88:89], v[4:5], v[146:147], v[44:45]
	v_pk_fma_f32 v[92:93], v[6:7], v[148:149], v[46:47]
	v_pk_fma_f32 v[146:147], v[0:1], v[150:151], v[40:41]
	v_lshlrev_b32_e32 v136, 16, v60
	v_and_b32_e32 v137, 0xffff0000, v60
	v_lshlrev_b32_e32 v134, 16, v61
	v_and_b32_e32 v135, 0xffff0000, v61
	v_pk_fma_f32 v[88:89], v[8:9], v[154:155], v[88:89]
	v_pk_fma_f32 v[92:93], v[10:11], v[156:157], v[92:93]
	v_pk_fma_f32 v[146:147], v[12:13], v[140:141], v[146:147]
	v_lshlrev_b32_e32 v128, 16, v56
	v_and_b32_e32 v129, 0xffff0000, v56
	v_lshlrev_b32_e32 v126, 16, v57
	v_and_b32_e32 v127, 0xffff0000, v57
	v_pk_fma_f32 v[88:89], v[16:17], v[136:137], v[88:89]
	v_pk_fma_f32 v[92:93], v[18:19], v[134:135], v[92:93]
	v_pk_fma_f32 v[146:147], v[20:21], v[132:133], v[146:147]
	v_pk_fma_f32 v[150:151], v[2:3], v[152:153], v[42:43]
	v_lshlrev_b32_e32 v120, 16, v68
	v_and_b32_e32 v121, 0xffff0000, v68
	v_lshlrev_b32_e32 v118, 16, v69
	v_and_b32_e32 v119, 0xffff0000, v69
	v_pk_fma_f32 v[88:89], v[24:25], v[128:129], v[88:89]
	v_pk_fma_f32 v[92:93], v[26:27], v[126:127], v[92:93]
	v_pk_fma_f32 v[146:147], v[28:29], v[124:125], v[146:147]
	v_pk_fma_f32 v[150:151], v[14:15], v[138:139], v[150:151]
	v_pk_fma_f32 v[88:89], v[32:33], v[120:121], v[88:89]
	v_pk_fma_f32 v[92:93], v[34:35], v[118:119], v[92:93]
	v_pk_fma_f32 v[146:147], v[36:37], v[116:117], v[146:147]
	v_pk_fma_f32 v[150:151], v[22:23], v[130:131], v[150:151]
	v_lshlrev_b32_e32 v112, 16, v64
	v_and_b32_e32 v113, 0xffff0000, v64
	v_lshlrev_b32_e32 v110, 16, v65
	v_and_b32_e32 v111, 0xffff0000, v65
	v_lshlrev_b32_e32 v64, 16, v94
	v_and_b32_e32 v65, 0xffff0000, v94
	v_lshlrev_b32_e32 v56, 16, v95
	v_and_b32_e32 v57, 0xffff0000, v95
	v_lshlrev_b32_e32 v68, 16, v90
	v_and_b32_e32 v69, 0xffff0000, v90
	v_lshlrev_b32_e32 v60, 16, v91
	v_and_b32_e32 v61, 0xffff0000, v91
	v_pk_mul_f32 v[90:91], v[88:89], s[48:49] op_sel_hi:[1,0]
	v_pk_mul_f32 v[94:95], v[92:93], s[48:49] op_sel_hi:[1,0]
	v_pk_mul_f32 v[148:149], v[146:147], s[48:49] op_sel_hi:[1,0]
	v_pk_fma_f32 v[150:151], v[30:31], v[122:123], v[150:151]
	v_exp_f32_e32 v90, v90
	v_exp_f32_e32 v91, v91
	v_exp_f32_e32 v94, v94
	v_exp_f32_e32 v95, v95
	v_exp_f32_e32 v148, v148
	v_exp_f32_e32 v149, v149
	v_pk_fma_f32 v[150:151], v[38:39], v[114:115], v[150:151]
	v_pk_add_f32 v[90:91], v[90:91], 1.0 op_sel_hi:[1,0]
	v_pk_mul_f32 v[152:153], v[150:151], s[48:49] op_sel_hi:[1,0]
	v_pk_add_f32 v[94:95], v[94:95], 1.0 op_sel_hi:[1,0]
	v_exp_f32_e32 v152, v152
	v_exp_f32_e32 v153, v153
	v_pk_add_f32 v[148:149], v[148:149], 1.0 op_sel_hi:[1,0]
	v_rcp_f32_e32 v90, v90
	v_rcp_f32_e32 v91, v91
	v_rcp_f32_e32 v94, v94
	v_rcp_f32_e32 v95, v95
	v_rcp_f32_e32 v148, v148
	v_rcp_f32_e32 v149, v149
	v_pk_add_f32 v[152:153], v[152:153], 1.0 op_sel_hi:[1,0]
	v_pk_mul_f32 v[88:89], v[88:89], v[90:91]
	v_rcp_f32_e32 v152, v152
	v_rcp_f32_e32 v153, v153
	v_pk_mul_f32 v[90:91], v[92:93], v[94:95]
	v_pk_mul_f32 v[92:93], v[146:147], v[148:149]
	v_mul_lo_u32 v145, v145, v143
	v_cvt_pk_bf16_f32 v88, v88, v89
	v_cvt_pk_bf16_f32 v89, v90, v91
	v_cvt_pk_bf16_f32 v90, v92, v93
	v_add_u32_e32 v92, v142, v145
	v_pk_mul_f32 v[94:95], v[150:151], v[152:153]
	v_pk_fma_f32 v[140:141], v[0:1], v[140:141], v[40:41]
	v_cvt_pk_bf16_f32 v91, v94, v95
	ds_write_b128 v92, v[88:91]
	v_pk_fma_f32 v[88:89], v[4:5], v[154:155], v[44:45]
	v_pk_fma_f32 v[92:93], v[6:7], v[156:157], v[46:47]
	v_pk_fma_f32 v[138:139], v[2:3], v[138:139], v[42:43]
	v_pk_fma_f32 v[88:89], v[8:9], v[136:137], v[88:89]
	v_pk_fma_f32 v[92:93], v[10:11], v[134:135], v[92:93]
	v_pk_fma_f32 v[140:141], v[12:13], v[132:133], v[140:141]
	v_pk_fma_f32 v[138:139], v[14:15], v[130:131], v[138:139]
	v_pk_fma_f32 v[88:89], v[16:17], v[128:129], v[88:89]
	v_pk_fma_f32 v[92:93], v[18:19], v[126:127], v[92:93]
	v_pk_fma_f32 v[140:141], v[20:21], v[124:125], v[140:141]
	v_pk_fma_f32 v[138:139], v[22:23], v[122:123], v[138:139]
	v_pk_fma_f32 v[88:89], v[24:25], v[120:121], v[88:89]
	v_pk_fma_f32 v[92:93], v[26:27], v[118:119], v[92:93]
	v_pk_fma_f32 v[140:141], v[28:29], v[116:117], v[140:141]
	v_pk_fma_f32 v[138:139], v[30:31], v[114:115], v[138:139]
	v_pk_fma_f32 v[88:89], v[32:33], v[112:113], v[88:89]
	v_pk_fma_f32 v[92:93], v[34:35], v[110:111], v[92:93]
	v_pk_fma_f32 v[140:141], v[36:37], v[108:109], v[140:141]
	v_pk_fma_f32 v[138:139], v[38:39], v[106:107], v[138:139]
	v_pk_mul_f32 v[90:91], v[88:89], s[48:49] op_sel_hi:[1,0]
	v_pk_mul_f32 v[94:95], v[92:93], s[48:49] op_sel_hi:[1,0]
	v_pk_mul_f32 v[146:147], v[140:141], s[48:49] op_sel_hi:[1,0]
	v_pk_mul_f32 v[148:149], v[138:139], s[48:49] op_sel_hi:[1,0]
	v_exp_f32_e32 v90, v90
	v_exp_f32_e32 v91, v91
	v_exp_f32_e32 v94, v94
	v_exp_f32_e32 v95, v95
	v_exp_f32_e32 v146, v146
	v_exp_f32_e32 v147, v147
	v_exp_f32_e32 v148, v148
	v_exp_f32_e32 v149, v149
	v_pk_add_f32 v[90:91], v[90:91], 1.0 op_sel_hi:[1,0]
	v_pk_add_f32 v[94:95], v[94:95], 1.0 op_sel_hi:[1,0]
	v_pk_add_f32 v[146:147], v[146:147], 1.0 op_sel_hi:[1,0]
	v_pk_add_f32 v[148:149], v[148:149], 1.0 op_sel_hi:[1,0]
	v_rcp_f32_e32 v90, v90
	v_rcp_f32_e32 v91, v91
	v_rcp_f32_e32 v94, v94
	v_rcp_f32_e32 v95, v95
	v_rcp_f32_e32 v146, v146
	v_rcp_f32_e32 v147, v147
	v_rcp_f32_e32 v148, v148
	v_rcp_f32_e32 v149, v149
	v_pk_mul_f32 v[88:89], v[88:89], v[90:91]
	v_pk_mul_f32 v[90:91], v[92:93], v[94:95]
	v_pk_mul_f32 v[92:93], v[140:141], v[146:147]
	v_pk_mul_f32 v[94:95], v[138:139], v[148:149]
	v_add_u32_e32 v138, v145, v143
	v_cvt_pk_bf16_f32 v88, v88, v89
	v_cvt_pk_bf16_f32 v89, v90, v91
	v_cvt_pk_bf16_f32 v90, v92, v93
	v_add_u32_e32 v92, v142, v138
	v_cvt_pk_bf16_f32 v91, v94, v95
	ds_write_b128 v92, v[88:91]
	v_pk_fma_f32 v[88:89], v[4:5], v[136:137], v[44:45]
	v_pk_fma_f32 v[92:93], v[6:7], v[134:135], v[46:47]
	v_pk_fma_f32 v[132:133], v[0:1], v[132:133], v[40:41]
	v_pk_fma_f32 v[130:131], v[2:3], v[130:131], v[42:43]
	v_pk_fma_f32 v[88:89], v[8:9], v[128:129], v[88:89]
	v_pk_fma_f32 v[92:93], v[10:11], v[126:127], v[92:93]
	v_pk_fma_f32 v[132:133], v[12:13], v[124:125], v[132:133]
	v_pk_fma_f32 v[130:131], v[14:15], v[122:123], v[130:131]
	v_pk_fma_f32 v[88:89], v[16:17], v[120:121], v[88:89]
	v_pk_fma_f32 v[92:93], v[18:19], v[118:119], v[92:93]
	v_pk_fma_f32 v[132:133], v[20:21], v[116:117], v[132:133]
	v_pk_fma_f32 v[130:131], v[22:23], v[114:115], v[130:131]
	v_pk_fma_f32 v[88:89], v[24:25], v[112:113], v[88:89]
	v_pk_fma_f32 v[92:93], v[26:27], v[110:111], v[92:93]
	v_pk_fma_f32 v[132:133], v[28:29], v[108:109], v[132:133]
	v_pk_fma_f32 v[130:131], v[30:31], v[106:107], v[130:131]
	v_pk_fma_f32 v[88:89], v[32:33], v[104:105], v[88:89]
	v_pk_fma_f32 v[92:93], v[34:35], v[102:103], v[92:93]
	v_pk_fma_f32 v[132:133], v[36:37], v[100:101], v[132:133]
	v_pk_fma_f32 v[130:131], v[38:39], v[98:99], v[130:131]
	v_pk_mul_f32 v[90:91], v[88:89], s[48:49] op_sel_hi:[1,0]
	v_pk_mul_f32 v[94:95], v[92:93], s[48:49] op_sel_hi:[1,0]
	v_pk_mul_f32 v[134:135], v[132:133], s[48:49] op_sel_hi:[1,0]
	v_pk_mul_f32 v[136:137], v[130:131], s[48:49] op_sel_hi:[1,0]
	v_exp_f32_e32 v90, v90
	v_exp_f32_e32 v91, v91
	v_exp_f32_e32 v94, v94
	v_exp_f32_e32 v95, v95
	v_exp_f32_e32 v134, v134
	v_exp_f32_e32 v135, v135
	v_exp_f32_e32 v136, v136
	v_exp_f32_e32 v137, v137
	v_pk_add_f32 v[90:91], v[90:91], 1.0 op_sel_hi:[1,0]
	v_pk_add_f32 v[94:95], v[94:95], 1.0 op_sel_hi:[1,0]
	v_pk_add_f32 v[134:135], v[134:135], 1.0 op_sel_hi:[1,0]
	v_pk_add_f32 v[136:137], v[136:137], 1.0 op_sel_hi:[1,0]
	v_rcp_f32_e32 v90, v90
	v_rcp_f32_e32 v91, v91
	v_rcp_f32_e32 v94, v94
	v_rcp_f32_e32 v95, v95
	v_rcp_f32_e32 v134, v134
	v_rcp_f32_e32 v135, v135
	v_rcp_f32_e32 v136, v136
	v_rcp_f32_e32 v137, v137
	v_pk_mul_f32 v[88:89], v[88:89], v[90:91]
	v_pk_mul_f32 v[90:91], v[92:93], v[94:95]
	v_pk_mul_f32 v[92:93], v[132:133], v[134:135]
	v_pk_mul_f32 v[94:95], v[130:131], v[136:137]
	v_add_u32_e32 v130, v138, v143
	v_cvt_pk_bf16_f32 v88, v88, v89
	v_cvt_pk_bf16_f32 v89, v90, v91
	v_cvt_pk_bf16_f32 v90, v92, v93
	v_add_u32_e32 v92, v142, v130
	v_cvt_pk_bf16_f32 v91, v94, v95
	ds_write_b128 v92, v[88:91]
	v_pk_fma_f32 v[88:89], v[4:5], v[128:129], v[44:45]
	v_pk_fma_f32 v[92:93], v[6:7], v[126:127], v[46:47]
	v_pk_fma_f32 v[124:125], v[0:1], v[124:125], v[40:41]
	v_pk_fma_f32 v[122:123], v[2:3], v[122:123], v[42:43]
	v_pk_fma_f32 v[88:89], v[8:9], v[120:121], v[88:89]
	v_pk_fma_f32 v[92:93], v[10:11], v[118:119], v[92:93]
	v_pk_fma_f32 v[124:125], v[12:13], v[116:117], v[124:125]
	v_pk_fma_f32 v[122:123], v[14:15], v[114:115], v[122:123]
	v_pk_fma_f32 v[88:89], v[16:17], v[112:113], v[88:89]
	v_pk_fma_f32 v[92:93], v[18:19], v[110:111], v[92:93]
	v_pk_fma_f32 v[124:125], v[20:21], v[108:109], v[124:125]
	v_pk_fma_f32 v[122:123], v[22:23], v[106:107], v[122:123]
	v_pk_fma_f32 v[88:89], v[24:25], v[104:105], v[88:89]
	v_pk_fma_f32 v[92:93], v[26:27], v[102:103], v[92:93]
	v_pk_fma_f32 v[124:125], v[28:29], v[100:101], v[124:125]
	v_pk_fma_f32 v[122:123], v[30:31], v[98:99], v[122:123]
	v_pk_fma_f32 v[88:89], v[32:33], v[76:77], v[88:89]
	v_pk_fma_f32 v[92:93], v[34:35], v[66:67], v[92:93]
	v_pk_fma_f32 v[124:125], v[36:37], v[54:55], v[124:125]
	v_pk_fma_f32 v[122:123], v[38:39], v[48:49], v[122:123]
	v_pk_mul_f32 v[90:91], v[88:89], s[48:49] op_sel_hi:[1,0]
	v_pk_mul_f32 v[94:95], v[92:93], s[48:49] op_sel_hi:[1,0]
	v_pk_mul_f32 v[126:127], v[124:125], s[48:49] op_sel_hi:[1,0]
	v_pk_mul_f32 v[128:129], v[122:123], s[48:49] op_sel_hi:[1,0]
	v_exp_f32_e32 v90, v90
	v_exp_f32_e32 v91, v91
	v_exp_f32_e32 v94, v94
	v_exp_f32_e32 v95, v95
	v_exp_f32_e32 v126, v126
	v_exp_f32_e32 v127, v127
	v_exp_f32_e32 v128, v128
	v_exp_f32_e32 v129, v129
	v_pk_add_f32 v[90:91], v[90:91], 1.0 op_sel_hi:[1,0]
	v_pk_add_f32 v[94:95], v[94:95], 1.0 op_sel_hi:[1,0]
	v_pk_add_f32 v[126:127], v[126:127], 1.0 op_sel_hi:[1,0]
	v_pk_add_f32 v[128:129], v[128:129], 1.0 op_sel_hi:[1,0]
	v_rcp_f32_e32 v90, v90
	v_rcp_f32_e32 v91, v91
	v_rcp_f32_e32 v94, v94
	v_rcp_f32_e32 v95, v95
	v_rcp_f32_e32 v126, v126
	v_rcp_f32_e32 v127, v127
	v_rcp_f32_e32 v128, v128
	v_rcp_f32_e32 v129, v129
	v_pk_mul_f32 v[88:89], v[88:89], v[90:91]
	v_pk_mul_f32 v[90:91], v[92:93], v[94:95]
	v_pk_mul_f32 v[92:93], v[124:125], v[126:127]
	v_pk_mul_f32 v[94:95], v[122:123], v[128:129]
	v_add_u32_e32 v122, v130, v143
	v_cvt_pk_bf16_f32 v88, v88, v89
	v_cvt_pk_bf16_f32 v89, v90, v91
	v_cvt_pk_bf16_f32 v90, v92, v93
	v_add_u32_e32 v92, v142, v122
	v_cvt_pk_bf16_f32 v91, v94, v95
	ds_write_b128 v92, v[88:91]
	v_pk_fma_f32 v[88:89], v[4:5], v[120:121], v[44:45]
	v_pk_fma_f32 v[92:93], v[6:7], v[118:119], v[46:47]
	v_pk_fma_f32 v[116:117], v[0:1], v[116:117], v[40:41]
	v_pk_fma_f32 v[114:115], v[2:3], v[114:115], v[42:43]
	v_pk_fma_f32 v[88:89], v[8:9], v[112:113], v[88:89]
	v_pk_fma_f32 v[92:93], v[10:11], v[110:111], v[92:93]
	v_pk_fma_f32 v[116:117], v[12:13], v[108:109], v[116:117]
	v_pk_fma_f32 v[114:115], v[14:15], v[106:107], v[114:115]
	v_pk_fma_f32 v[88:89], v[16:17], v[104:105], v[88:89]
	v_pk_fma_f32 v[92:93], v[18:19], v[102:103], v[92:93]
	v_pk_fma_f32 v[116:117], v[20:21], v[100:101], v[116:117]
	v_pk_fma_f32 v[114:115], v[22:23], v[98:99], v[114:115]
	v_pk_fma_f32 v[88:89], v[24:25], v[76:77], v[88:89]
	v_pk_fma_f32 v[92:93], v[26:27], v[66:67], v[92:93]
	v_pk_fma_f32 v[116:117], v[28:29], v[54:55], v[116:117]
	v_pk_fma_f32 v[114:115], v[30:31], v[48:49], v[114:115]
	v_pk_fma_f32 v[88:89], v[32:33], v[78:79], v[88:89]
	v_pk_fma_f32 v[92:93], v[34:35], v[70:71], v[92:93]
	v_pk_fma_f32 v[116:117], v[36:37], v[58:59], v[116:117]
	v_pk_fma_f32 v[114:115], v[38:39], v[50:51], v[114:115]
	v_pk_mul_f32 v[90:91], v[88:89], s[48:49] op_sel_hi:[1,0]
	v_pk_mul_f32 v[94:95], v[92:93], s[48:49] op_sel_hi:[1,0]
	v_pk_mul_f32 v[118:119], v[116:117], s[48:49] op_sel_hi:[1,0]
	v_pk_mul_f32 v[120:121], v[114:115], s[48:49] op_sel_hi:[1,0]
	v_exp_f32_e32 v90, v90
	v_exp_f32_e32 v91, v91
	v_exp_f32_e32 v94, v94
	v_exp_f32_e32 v95, v95
	v_exp_f32_e32 v118, v118
	v_exp_f32_e32 v119, v119
	v_exp_f32_e32 v120, v120
	v_exp_f32_e32 v121, v121
	v_pk_add_f32 v[90:91], v[90:91], 1.0 op_sel_hi:[1,0]
	v_pk_add_f32 v[94:95], v[94:95], 1.0 op_sel_hi:[1,0]
	v_pk_add_f32 v[118:119], v[118:119], 1.0 op_sel_hi:[1,0]
	v_pk_add_f32 v[120:121], v[120:121], 1.0 op_sel_hi:[1,0]
	v_rcp_f32_e32 v90, v90
	v_rcp_f32_e32 v91, v91
	v_rcp_f32_e32 v94, v94
	v_rcp_f32_e32 v95, v95
	v_rcp_f32_e32 v118, v118
	v_rcp_f32_e32 v119, v119
	v_rcp_f32_e32 v120, v120
	v_rcp_f32_e32 v121, v121
	v_pk_mul_f32 v[88:89], v[88:89], v[90:91]
	v_pk_mul_f32 v[90:91], v[92:93], v[94:95]
	v_pk_mul_f32 v[92:93], v[116:117], v[118:119]
	v_pk_mul_f32 v[94:95], v[114:115], v[120:121]
	v_add_u32_e32 v114, v122, v143
	v_cvt_pk_bf16_f32 v88, v88, v89
	v_cvt_pk_bf16_f32 v89, v90, v91
	v_cvt_pk_bf16_f32 v90, v92, v93
	v_add_u32_e32 v92, v142, v114
	v_cvt_pk_bf16_f32 v91, v94, v95
	ds_write_b128 v92, v[88:91]
	v_pk_fma_f32 v[88:89], v[4:5], v[112:113], v[44:45]
	v_pk_fma_f32 v[92:93], v[6:7], v[110:111], v[46:47]
	v_pk_fma_f32 v[108:109], v[0:1], v[108:109], v[40:41]
	v_pk_fma_f32 v[106:107], v[2:3], v[106:107], v[42:43]
	v_pk_fma_f32 v[88:89], v[8:9], v[104:105], v[88:89]
	v_pk_fma_f32 v[92:93], v[10:11], v[102:103], v[92:93]
	v_pk_fma_f32 v[108:109], v[12:13], v[100:101], v[108:109]
	v_pk_fma_f32 v[106:107], v[14:15], v[98:99], v[106:107]
	v_pk_fma_f32 v[88:89], v[16:17], v[76:77], v[88:89]
	v_pk_fma_f32 v[92:93], v[18:19], v[66:67], v[92:93]
	v_pk_fma_f32 v[108:109], v[20:21], v[54:55], v[108:109]
	v_pk_fma_f32 v[106:107], v[22:23], v[48:49], v[106:107]
	v_pk_fma_f32 v[88:89], v[24:25], v[78:79], v[88:89]
	v_pk_fma_f32 v[92:93], v[26:27], v[70:71], v[92:93]
	v_pk_fma_f32 v[108:109], v[28:29], v[58:59], v[108:109]
	v_pk_fma_f32 v[106:107], v[30:31], v[50:51], v[106:107]
	v_pk_fma_f32 v[88:89], v[32:33], v[84:85], v[88:89]
	v_pk_fma_f32 v[92:93], v[34:35], v[72:73], v[92:93]
	v_pk_fma_f32 v[108:109], v[36:37], v[62:63], v[108:109]
	v_pk_fma_f32 v[106:107], v[38:39], v[52:53], v[106:107]
	v_pk_mul_f32 v[90:91], v[88:89], s[48:49] op_sel_hi:[1,0]
	v_pk_mul_f32 v[94:95], v[92:93], s[48:49] op_sel_hi:[1,0]
	v_pk_mul_f32 v[110:111], v[108:109], s[48:49] op_sel_hi:[1,0]
	v_pk_mul_f32 v[112:113], v[106:107], s[48:49] op_sel_hi:[1,0]
	v_exp_f32_e32 v90, v90
	v_exp_f32_e32 v91, v91
	v_exp_f32_e32 v94, v94
	v_exp_f32_e32 v95, v95
	v_exp_f32_e32 v110, v110
	v_exp_f32_e32 v111, v111
	v_exp_f32_e32 v112, v112
	v_exp_f32_e32 v113, v113
	v_pk_add_f32 v[90:91], v[90:91], 1.0 op_sel_hi:[1,0]
	v_pk_add_f32 v[94:95], v[94:95], 1.0 op_sel_hi:[1,0]
	v_pk_add_f32 v[110:111], v[110:111], 1.0 op_sel_hi:[1,0]
	v_pk_add_f32 v[112:113], v[112:113], 1.0 op_sel_hi:[1,0]
	v_rcp_f32_e32 v90, v90
	v_rcp_f32_e32 v91, v91
	v_rcp_f32_e32 v94, v94
	v_rcp_f32_e32 v95, v95
	v_rcp_f32_e32 v110, v110
	v_rcp_f32_e32 v111, v111
	v_rcp_f32_e32 v112, v112
	v_rcp_f32_e32 v113, v113
	v_pk_mul_f32 v[88:89], v[88:89], v[90:91]
	v_pk_mul_f32 v[90:91], v[92:93], v[94:95]
	v_pk_mul_f32 v[92:93], v[108:109], v[110:111]
	v_pk_mul_f32 v[94:95], v[106:107], v[112:113]
	v_add_u32_e32 v106, v114, v143
	v_cvt_pk_bf16_f32 v88, v88, v89
	v_cvt_pk_bf16_f32 v89, v90, v91
	v_cvt_pk_bf16_f32 v90, v92, v93
	v_add_u32_e32 v92, v142, v106
	v_cvt_pk_bf16_f32 v91, v94, v95
	ds_write_b128 v92, v[88:91]
	v_pk_fma_f32 v[88:89], v[4:5], v[104:105], v[44:45]
	v_pk_fma_f32 v[92:93], v[6:7], v[102:103], v[46:47]
	v_pk_fma_f32 v[100:101], v[0:1], v[100:101], v[40:41]
	v_pk_fma_f32 v[88:89], v[8:9], v[76:77], v[88:89]
	v_pk_fma_f32 v[92:93], v[10:11], v[66:67], v[92:93]
	v_pk_fma_f32 v[100:101], v[12:13], v[54:55], v[100:101]
	v_pk_fma_f32 v[88:89], v[16:17], v[78:79], v[88:89]
	v_pk_fma_f32 v[92:93], v[18:19], v[70:71], v[92:93]
	v_pk_fma_f32 v[100:101], v[20:21], v[58:59], v[100:101]
	v_pk_fma_f32 v[98:99], v[2:3], v[98:99], v[42:43]
	v_pk_fma_f32 v[54:55], v[0:1], v[54:55], v[40:41]
	v_pk_fma_f32 v[88:89], v[24:25], v[84:85], v[88:89]
	v_pk_fma_f32 v[92:93], v[26:27], v[72:73], v[92:93]
	v_pk_fma_f32 v[100:101], v[28:29], v[62:63], v[100:101]
	v_pk_fma_f32 v[98:99], v[14:15], v[48:49], v[98:99]
	v_pk_fma_f32 v[76:77], v[4:5], v[76:77], v[44:45]
	v_pk_fma_f32 v[66:67], v[6:7], v[66:67], v[46:47]
	v_pk_fma_f32 v[54:55], v[12:13], v[58:59], v[54:55]
	v_pk_fma_f32 v[48:49], v[2:3], v[48:49], v[42:43]
	v_pk_fma_f32 v[88:89], v[32:33], v[82:83], v[88:89]
	v_pk_fma_f32 v[92:93], v[34:35], v[74:75], v[92:93]
	v_pk_fma_f32 v[100:101], v[36:37], v[64:65], v[100:101]
	v_pk_fma_f32 v[76:77], v[8:9], v[78:79], v[76:77]
	v_pk_fma_f32 v[66:67], v[10:11], v[70:71], v[66:67]
	v_pk_fma_f32 v[54:55], v[20:21], v[62:63], v[54:55]
	v_pk_fma_f32 v[48:49], v[14:15], v[50:51], v[48:49]
	v_pk_mul_f32 v[90:91], v[88:89], s[48:49] op_sel_hi:[1,0]
	v_pk_mul_f32 v[94:95], v[92:93], s[48:49] op_sel_hi:[1,0]
	v_pk_mul_f32 v[102:103], v[100:101], s[48:49] op_sel_hi:[1,0]
	v_pk_fma_f32 v[98:99], v[22:23], v[50:51], v[98:99]
	v_pk_fma_f32 v[76:77], v[16:17], v[84:85], v[76:77]
	v_pk_fma_f32 v[66:67], v[18:19], v[72:73], v[66:67]
	v_pk_fma_f32 v[54:55], v[28:29], v[64:65], v[54:55]
	v_pk_fma_f32 v[48:49], v[22:23], v[52:53], v[48:49]
	v_exp_f32_e32 v90, v90
	v_exp_f32_e32 v91, v91
	v_exp_f32_e32 v94, v94
	v_exp_f32_e32 v95, v95
	v_exp_f32_e32 v102, v102
	v_exp_f32_e32 v103, v103
	v_pk_fma_f32 v[98:99], v[30:31], v[52:53], v[98:99]
	v_pk_fma_f32 v[76:77], v[24:25], v[82:83], v[76:77]
	v_pk_fma_f32 v[66:67], v[26:27], v[74:75], v[66:67]
	v_pk_fma_f32 v[54:55], v[36:37], v[68:69], v[54:55]
	v_pk_fma_f32 v[48:49], v[30:31], v[56:57], v[48:49]
	v_pk_fma_f32 v[98:99], v[38:39], v[56:57], v[98:99]
	v_pk_fma_f32 v[76:77], v[32:33], v[86:87], v[76:77]
	v_pk_fma_f32 v[66:67], v[34:35], v[80:81], v[66:67]
	v_pk_mul_f32 v[58:59], v[54:55], s[48:49] op_sel_hi:[1,0]
	v_pk_fma_f32 v[48:49], v[38:39], v[60:61], v[48:49]
	v_pk_mul_f32 v[104:105], v[98:99], s[48:49] op_sel_hi:[1,0]
	v_pk_mul_f32 v[78:79], v[76:77], s[48:49] op_sel_hi:[1,0]
	v_pk_mul_f32 v[70:71], v[66:67], s[48:49] op_sel_hi:[1,0]
	v_exp_f32_e32 v58, v58
	v_exp_f32_e32 v59, v59
	v_pk_mul_f32 v[50:51], v[48:49], s[48:49] op_sel_hi:[1,0]
	v_exp_f32_e32 v104, v104
	v_exp_f32_e32 v105, v105
	v_exp_f32_e32 v78, v78
	v_exp_f32_e32 v79, v79
	v_exp_f32_e32 v70, v70
	v_exp_f32_e32 v71, v71
	v_exp_f32_e32 v50, v50
	v_exp_f32_e32 v51, v51
	v_pk_add_f32 v[90:91], v[90:91], 1.0 op_sel_hi:[1,0]
	v_pk_add_f32 v[94:95], v[94:95], 1.0 op_sel_hi:[1,0]
	v_pk_add_f32 v[102:103], v[102:103], 1.0 op_sel_hi:[1,0]
	v_rcp_f32_e32 v90, v90
	v_rcp_f32_e32 v91, v91
	v_rcp_f32_e32 v94, v94
	v_rcp_f32_e32 v95, v95
	v_rcp_f32_e32 v102, v102
	v_rcp_f32_e32 v103, v103
	v_pk_add_f32 v[52:53], v[58:59], 1.0 op_sel_hi:[1,0]
	v_pk_add_f32 v[104:105], v[104:105], 1.0 op_sel_hi:[1,0]
	v_pk_add_f32 v[72:73], v[78:79], 1.0 op_sel_hi:[1,0]
	v_pk_add_f32 v[70:71], v[70:71], 1.0 op_sel_hi:[1,0]
	v_rcp_f32_e32 v52, v52
	v_rcp_f32_e32 v53, v53
	v_pk_add_f32 v[50:51], v[50:51], 1.0 op_sel_hi:[1,0]
	v_rcp_f32_e32 v104, v104
	v_rcp_f32_e32 v105, v105
	v_rcp_f32_e32 v72, v72
	v_rcp_f32_e32 v73, v73
	v_rcp_f32_e32 v70, v70
	v_rcp_f32_e32 v71, v71
	v_rcp_f32_e32 v50, v50
	v_rcp_f32_e32 v51, v51
	v_pk_mul_f32 v[88:89], v[88:89], v[90:91]
	v_pk_mul_f32 v[90:91], v[92:93], v[94:95]
	v_pk_mul_f32 v[92:93], v[100:101], v[102:103]
	v_cvt_pk_bf16_f32 v88, v88, v89
	v_cvt_pk_bf16_f32 v89, v90, v91
	v_pk_mul_f32 v[52:53], v[54:55], v[52:53]
	v_cvt_pk_bf16_f32 v90, v92, v93
	v_add_u32_e32 v92, v106, v143
	v_add_u32_e32 v93, v142, v92
	s_xor_b64 s[4:5], s[4:5], -1
	v_pk_mul_f32 v[94:95], v[98:99], v[104:105]
	v_pk_mul_f32 v[56:57], v[76:77], v[72:73]
	v_cvt_pk_bf16_f32 v91, v94, v95
	ds_write_b128 v93, v[88:91]
	v_pk_mul_f32 v[58:59], v[66:67], v[70:71]
	v_pk_mul_f32 v[54:55], v[48:49], v[50:51]
	v_cvt_pk_bf16_f32 v48, v56, v57
	v_cvt_pk_bf16_f32 v49, v58, v59
	v_cvt_pk_bf16_f32 v50, v52, v53
	v_add3_u32 v52, v92, v143, v142
	s_mov_b32 s0, 8
	s_andn2_b64 vcc, exec, s[4:5]
	s_mov_b64 s[4:5], 0
	v_cvt_pk_bf16_f32 v51, v54, v55
	ds_write_b128 v52, v[48:51]
	s_cbranch_vccz .LBB0_850
.Lcv5_second:
	s_waitcnt vmcnt(0)
	v_readfirstlane_b32 s100, v144
	s_nop 0
	s_add_i32 s100, s100, s9
	s_add_i32 s100, s100, 8
	s_cmp_lt_i32 s100, s8
	s_cselect_b64 vcc, -1, 0
	s_add_i32 s100, s100, 1
	v_cndmask_b32_e32 v52, 0, v208, vcc
	v_cndmask_b32_e32 v53, 0, v209, vcc
	v_cndmask_b32_e32 v54, 0, v210, vcc
	v_cndmask_b32_e32 v55, 0, v211, vcc
	s_cmp_lt_i32 s100, s8
	s_cselect_b64 vcc, -1, 0
	s_add_i32 s100, s100, 1
	v_cndmask_b32_e32 v48, 0, v212, vcc
	v_cndmask_b32_e32 v49, 0, v213, vcc
	v_cndmask_b32_e32 v50, 0, v214, vcc
	v_cndmask_b32_e32 v51, 0, v215, vcc
	s_cmp_lt_i32 s100, s8
	s_cselect_b64 vcc, -1, 0
	s_add_i32 s100, s100, 1
	v_cndmask_b32_e32 v60, 0, v216, vcc
	v_cndmask_b32_e32 v61, 0, v217, vcc
	v_cndmask_b32_e32 v62, 0, v218, vcc
	v_cndmask_b32_e32 v63, 0, v219, vcc
	s_cmp_lt_i32 s100, s8
	s_cselect_b64 vcc, -1, 0
	s_add_i32 s100, s100, 1
	v_cndmask_b32_e32 v56, 0, v220, vcc
	v_cndmask_b32_e32 v57, 0, v221, vcc
	v_cndmask_b32_e32 v58, 0, v222, vcc
	v_cndmask_b32_e32 v59, 0, v223, vcc
	s_cmp_lt_i32 s100, s8
	s_cselect_b64 vcc, -1, 0
	s_add_i32 s100, s100, 1
	v_cndmask_b32_e32 v68, 0, v224, vcc
	v_cndmask_b32_e32 v69, 0, v225, vcc
	v_cndmask_b32_e32 v70, 0, v226, vcc
	v_cndmask_b32_e32 v71, 0, v227, vcc
	s_cmp_lt_i32 s100, s8
	s_cselect_b64 vcc, -1, 0
	s_add_i32 s100, s100, 1
	v_cndmask_b32_e32 v64, 0, v228, vcc
	v_cndmask_b32_e32 v65, 0, v229, vcc
	v_cndmask_b32_e32 v66, 0, v230, vcc
	v_cndmask_b32_e32 v67, 0, v231, vcc
	s_cmp_lt_i32 s100, s8
	s_cselect_b64 vcc, -1, 0
	s_add_i32 s100, s100, 1
	v_cndmask_b32_e32 v76, 0, v232, vcc
	v_cndmask_b32_e32 v77, 0, v233, vcc
	v_cndmask_b32_e32 v78, 0, v234, vcc
	v_cndmask_b32_e32 v79, 0, v235, vcc
	s_cmp_lt_i32 s100, s8
	s_cselect_b64 vcc, -1, 0
	s_add_i32 s100, s100, 1
	v_cndmask_b32_e32 v72, 0, v236, vcc
	v_cndmask_b32_e32 v73, 0, v237, vcc
	v_cndmask_b32_e32 v74, 0, v238, vcc
	v_cndmask_b32_e32 v75, 0, v239, vcc
	s_cmp_lt_i32 s100, s8
	s_cselect_b64 vcc, -1, 0
	s_add_i32 s100, s100, 1
	v_cndmask_b32_e32 v84, 0, v240, vcc
	v_cndmask_b32_e32 v85, 0, v241, vcc
	v_cndmask_b32_e32 v86, 0, v242, vcc
	v_cndmask_b32_e32 v87, 0, v243, vcc
	s_cmp_lt_i32 s100, s8
	s_cselect_b64 vcc, -1, 0
	s_add_i32 s100, s100, 1
	v_cndmask_b32_e32 v80, 0, v244, vcc
	v_cndmask_b32_e32 v81, 0, v245, vcc
	v_cndmask_b32_e32 v82, 0, v246, vcc
	v_cndmask_b32_e32 v83, 0, v247, vcc
	s_cmp_lt_i32 s100, s8
	s_cselect_b64 vcc, -1, 0
	s_add_i32 s100, s100, 1
	v_cndmask_b32_e32 v92, 0, v162, vcc
	v_cndmask_b32_e32 v93, 0, v163, vcc
	v_cndmask_b32_e32 v94, 0, v164, vcc
	v_cndmask_b32_e32 v95, 0, v165, vcc
	s_cmp_lt_i32 s100, s8
	s_cselect_b64 vcc, -1, 0
	s_add_i32 s100, s100, 1
	v_cndmask_b32_e32 v88, 0, v166, vcc
	v_cndmask_b32_e32 v89, 0, v167, vcc
	v_cndmask_b32_e32 v90, 0, v168, vcc
	v_cndmask_b32_e32 v91, 0, v169, vcc
	v_or_b32_e32 v145, 8, v144
	s_branch .Lcv5_go

.LBB0_947:
	s_or_b64 exec, exec, s[0:1]
	s_waitcnt vmcnt(1)
	v_mov_b32_e32 v1, v195
	s_cmpk_lt_i32 s2, 0x200
	s_waitcnt lgkmcnt(0)
	s_barrier
	s_nop 0
	s_nop 0
	s_nop 0
	s_nop 0
	s_nop 0
	s_nop 0
	s_nop 0
	s_nop 0
	s_cselect_b64 s[4:5], -1, 0
	s_cmpk_gt_i32 s2, 0x1ff
	v_readfirstlane_b32 s3, v1
	s_cbranch_scc1 .LBB0_950
	s_and_b32 s8, s2, 7
	s_bfe_u32 s1, s2, 0x50003
	s_cmpk_gt_i32 s2, 0xff
	s_cbranch_scc0 .LBB0_951
	s_lshl_b32 s0, s8, 1
	s_bfe_u32 s6, s2, 0x10003
	s_or_b32 s0, s0, s6
	s_lshr_b32 s73, s1, 3
	s_or_b32 s0, s0, 64
	s_bfe_u32 s38, s2, 0x20004
	s_cmp_gt_u32 s1, 15
	s_cselect_b32 s6, 0x2800000, 0
	s_lshl_b32 s12, s73, 10
	s_mov_b32 s11, 0
	s_and_b32 s7, s12, 0x400
	s_or_b32 s10, s6, s7
	s_mov_b32 s13, s11
	s_mov_b32 s74, 8
	s_cbranch_execz .LBB0_952
	s_branch .LBB0_953
